# v119 + masked attention loop: LDS-DMA issue moved from the step head into the P.V phase VALU gaps (skip path issues it in a stub); placement-matched
# baseline (speedup 1.0000x reference)
; #define ATT_LAS __attribute__((address_space(3)))
; __device__ __forceinline__ unsigned pk_bf16(float lo, float hi) { unsigned r; asm volatile("v_cvt_pk_bf16_f32 %0, %1, %2" : "=v"(r) : "v"(lo), "v"(hi)); return r; }
; __device__ __forceinline__ void attn_unit(int uv, const float* sink_l, const bf16_t* P, bf16_t* Y, ATT_LAS unsigned char* lds, const float* rpb_l, const float* qn_l, const float* kn_l) {
;     ...
;             if (t + 1 < nlat) { const size_t ro = (size_t)ATT_TROW(t + 5) * PITCH; kreg = *(const u32x4*)(kg + ro); vreg = *(const u32x4*)(vg + ro); }
;     ...
;                 float sum = 0.f;
; #pragma unroll
;                 for (int r = 0; r < 16; ++r) { p0[r] = __builtin_amdgcn_exp2f(p0[r] - m); p1[r] = __builtin_amdgcn_exp2f(p1[r] - m); sum += p0[r] + p1[r]; }
;                 lsum += sum;
;                 u32x4 pw[4];
; #pragma unroll
;                 for (int j = 0; j < 4; ++j) { pw[0][j] = pk_bf16(p0[2 * j], p0[2 * j + 1]); pw[1][j] = pk_bf16(p0[8 + 2 * j], p0[8 + 2 * j + 1]);
;                                               pw[2][j] = pk_bf16(p1[2 * j], p1[2 * j + 1]); pw[3][j] = pk_bf16(p1[8 + 2 * j], p1[8 + 2 * j + 1]); }
;                 const ATT_LAS unsigned char* vb = Vb + vlane;
; #pragma unroll
;                 for (int s = 0; s < 4; ++s) {
;                     const bf16x8 pa = __builtin_bit_cast(bf16x8, pw[s]);
;                     { const s16x4 lo = vtr(vb + s * 1024), h4 = vtr(vb + s * 1024 + 512);
;                       const bf16x8 vf = (bf16x8){lo[0], lo[1], lo[2], lo[3], h4[0], h4[1], h4[2], h4[3]};
;                       o0 = __builtin_amdgcn_mfma_f32_32x32x16_bf16(vf, pa, o0, 0, 0, 0); }
;                     { const s16x4 lo = vtr(vb + 4096 + s * 1024), h4 = vtr(vb + 4096 + s * 1024 + 512);
;                       const bf16x8 vf = (bf16x8){lo[0], lo[1], lo[2], lo[3], h4[0], h4[1], h4[2], h4[3]};
;                       o1 = __builtin_amdgcn_mfma_f32_32x32x16_bf16(vf, pa, o1, 0, 0, 0); }
;                 }
.Lnb_ctx_norescale:
	v_sub_f32_e32 v80, v80, v202
	v_sub_f32_e32 v81, v81, v202
	v_sub_f32_e32 v82, v82, v202
	v_sub_f32_e32 v83, v83, v202
	v_sub_f32_e32 v84, v84, v202
	v_sub_f32_e32 v85, v85, v202
	v_sub_f32_e32 v86, v86, v202
	v_sub_f32_e32 v87, v87, v202
	v_sub_f32_e32 v88, v88, v202
	v_sub_f32_e32 v89, v89, v202
	v_sub_f32_e32 v90, v90, v202
	v_sub_f32_e32 v91, v91, v202
	v_sub_f32_e32 v92, v92, v202
	v_sub_f32_e32 v93, v93, v202
	v_sub_f32_e32 v94, v94, v202
	v_sub_f32_e32 v95, v95, v202
	v_sub_f32_e32 v48, v48, v202
	v_sub_f32_e32 v49, v49, v202
	v_sub_f32_e32 v50, v50, v202
	v_sub_f32_e32 v51, v51, v202
	v_sub_f32_e32 v52, v52, v202
	v_sub_f32_e32 v53, v53, v202
	v_sub_f32_e32 v54, v54, v202
	v_sub_f32_e32 v55, v55, v202
	v_sub_f32_e32 v56, v56, v202
	v_sub_f32_e32 v57, v57, v202
	v_sub_f32_e32 v58, v58, v202
	v_sub_f32_e32 v59, v59, v202
	v_sub_f32_e32 v60, v60, v202
	v_sub_f32_e32 v61, v61, v202
	v_sub_f32_e32 v62, v62, v202
	v_sub_f32_e32 v63, v63, v202
	v_exp_f32_e32 v80, v80
	v_exp_f32_e32 v81, v81
	v_exp_f32_e32 v82, v82
	v_exp_f32_e32 v83, v83
	v_exp_f32_e32 v84, v84
	v_exp_f32_e32 v85, v85
	v_exp_f32_e32 v86, v86
	v_exp_f32_e32 v87, v87
	s_nop 0
	v_cvt_pk_bf16_f32 v32, v80, v81
	v_cvt_pk_bf16_f32 v33, v82, v83
	v_cvt_pk_bf16_f32 v34, v84, v85
	v_cvt_pk_bf16_f32 v35, v86, v87
	s_nop 1
	s_waitcnt lgkmcnt(0)
	v_mfma_f32_32x32x16_bf16 v[0:15], v[160:163], v[32:35], v[0:15]
	v_exp_f32_e32 v88, v88
	v_exp_f32_e32 v89, v89
	v_exp_f32_e32 v90, v90
	v_exp_f32_e32 v91, v91
	v_mfma_f32_32x32x16_bf16 v[16:31], v[176:179], v[32:35], v[16:31]
	s_cmp_lg_u64 s[82:83], 0
	s_cbranch_scc0 .Lmkdk_ctx
	s_add_i32 s80, s32, 2
	s_cmp_ge_u32 s80, 3
	s_cselect_b32 s81, 3, 0
	s_sub_i32 s80, s80, s81
	s_lshl_b32 s81, s80, 13
	s_add_i32 s81, s81, s100
	s_mov_b32 m0, s81
	s_nop 0
	global_load_lds_dwordx4 v[112:113], off
	v_lshl_add_u64 v[112:113], v[112:113], 0, s[98:99]
.Lmkdk_ctx:
	v_exp_f32_e32 v92, v92
	v_exp_f32_e32 v93, v93
	v_exp_f32_e32 v94, v94
	v_exp_f32_e32 v95, v95
	s_nop 0
	v_cvt_pk_bf16_f32 v36, v88, v89
	v_cvt_pk_bf16_f32 v37, v90, v91
	v_cvt_pk_bf16_f32 v38, v92, v93
	v_cvt_pk_bf16_f32 v39, v94, v95
	v_mov_b32_e32 v204, v80
	v_mov_b32_e32 v205, v81
	v_mov_b32_e32 v208, v82
	v_mov_b32_e32 v209, v83
	v_add_f32_e32 v204, v204, v84
	v_add_f32_e32 v205, v205, v85
	v_add_f32_e32 v208, v208, v86
	v_add_f32_e32 v209, v209, v87
	v_mfma_f32_32x32x16_bf16 v[0:15], v[164:167], v[36:39], v[0:15]
	v_exp_f32_e32 v48, v48
	v_exp_f32_e32 v49, v49
	v_exp_f32_e32 v50, v50
	v_exp_f32_e32 v51, v51
	v_mfma_f32_32x32x16_bf16 v[16:31], v[180:183], v[36:39], v[16:31]
	s_cmp_lg_u64 s[82:83], 0
	s_cbranch_scc0 .Lmkdv_ctx
	s_add_i32 s80, s32, 2
	s_cmp_ge_u32 s80, 3
	s_cselect_b32 s81, 3, 0
	s_sub_i32 s80, s80, s81
	s_lshl_b32 s81, s80, 13
	s_add_i32 s96, s81, 0x6000
	s_cmp_eq_u32 s80, 2
	s_cselect_b32 s80, 0xc000, s96
	s_add_i32 s80, s80, s100
	s_mov_b32 m0, s80
	s_nop 0
	global_load_lds_dwordx4 v[114:115], off
	v_lshl_add_u64 v[114:115], v[114:115], 0, s[98:99]
.Lmkdv_ctx:
	v_exp_f32_e32 v52, v52
	v_exp_f32_e32 v53, v53
	v_exp_f32_e32 v54, v54
	v_exp_f32_e32 v55, v55
	s_nop 0
	v_cvt_pk_bf16_f32 v40, v48, v49
	v_cvt_pk_bf16_f32 v41, v50, v51
	v_cvt_pk_bf16_f32 v42, v52, v53
	v_cvt_pk_bf16_f32 v43, v54, v55
	v_add_f32_e32 v204, v204, v88
	v_add_f32_e32 v205, v205, v89
	v_add_f32_e32 v208, v208, v90
	v_add_f32_e32 v209, v209, v91
	v_add_f32_e32 v204, v204, v92
	v_add_f32_e32 v205, v205, v93
	v_add_f32_e32 v208, v208, v94
	v_add_f32_e32 v209, v209, v95
	v_mfma_f32_32x32x16_bf16 v[0:15], v[168:171], v[40:43], v[0:15]
	v_exp_f32_e32 v56, v56
	v_exp_f32_e32 v57, v57
	v_exp_f32_e32 v58, v58
	v_exp_f32_e32 v59, v59
	v_mfma_f32_32x32x16_bf16 v[16:31], v[184:187], v[40:43], v[16:31]
	v_exp_f32_e32 v60, v60
	v_exp_f32_e32 v61, v61
	v_exp_f32_e32 v62, v62
	v_exp_f32_e32 v63, v63
	s_nop 0
	v_cvt_pk_bf16_f32 v44, v56, v57
	v_cvt_pk_bf16_f32 v45, v58, v59
	v_cvt_pk_bf16_f32 v46, v60, v61
	v_cvt_pk_bf16_f32 v47, v62, v63
	v_add_f32_e32 v204, v204, v48
	v_add_f32_e32 v205, v205, v49
	v_add_f32_e32 v208, v208, v50
	v_add_f32_e32 v209, v209, v51
	v_add_f32_e32 v204, v204, v52
	v_add_f32_e32 v205, v205, v53
	v_add_f32_e32 v208, v208, v54
	v_add_f32_e32 v209, v209, v55
	v_mfma_f32_32x32x16_bf16 v[0:15], v[172:175], v[44:47], v[0:15]
	v_mfma_f32_32x32x16_bf16 v[16:31], v[188:191], v[44:47], v[16:31]
	v_add_f32_e32 v204, v204, v56
	v_add_f32_e32 v205, v205, v57
	v_add_f32_e32 v208, v208, v58
	v_add_f32_e32 v209, v209, v59
	v_add_f32_e32 v204, v204, v60
	v_add_f32_e32 v205, v205, v61
	v_add_f32_e32 v208, v208, v62
	v_add_f32_e32 v209, v209, v63
	v_add_f32_e32 v204, v204, v205
	v_add_f32_e32 v208, v208, v209
	v_add_f32_e32 v204, v204, v208
	v_add_f32_e32 v124, v124, v204
	s_branch .Lmsk_tail

; #define ATT_LAS __attribute__((address_space(3)))
; __device__ __forceinline__ unsigned pk_bf16(float lo, float hi) { unsigned r; asm volatile("v_cvt_pk_bf16_f32 %0, %1, %2" : "=v"(r) : "v"(lo), "v"(hi)); return r; }
; __device__ __forceinline__ void attn_unit(int uv, const float* sink_l, const bf16_t* P, bf16_t* Y, ATT_LAS unsigned char* lds, const float* rpb_l, const float* qn_l, const float* kn_l) {
;     ...
;                 float sum = 0.f;
; #pragma unroll
;                 for (int r = 0; r < 16; ++r) { p0[r] = __builtin_amdgcn_exp2f(p0[r] - m); p1[r] = __builtin_amdgcn_exp2f(p1[r] - m); sum += p0[r] + p1[r]; }
;                 lsum += sum;
;                 u32x4 pw[4];
; #pragma unroll
;                 for (int j = 0; j < 4; ++j) { pw[0][j] = pk_bf16(p0[2 * j], p0[2 * j + 1]); pw[1][j] = pk_bf16(p0[8 + 2 * j], p0[8 + 2 * j + 1]);
;                                               pw[2][j] = pk_bf16(p1[2 * j], p1[2 * j + 1]); pw[3][j] = pk_bf16(p1[8 + 2 * j], p1[8 + 2 * j + 1]); }
;                 const ATT_LAS unsigned char* vb = Vb + vlane;
; #pragma unroll
;                 for (int s = 0; s < 4; ++s) {
;                     const bf16x8 pa = __builtin_bit_cast(bf16x8, pw[s]);
;                     { const s16x4 lo = vtr(vb + s * 1024), h4 = vtr(vb + s * 1024 + 512);
;                       const bf16x8 vf = (bf16x8){lo[0], lo[1], lo[2], lo[3], h4[0], h4[1], h4[2], h4[3]};
;                       o0 = __builtin_amdgcn_mfma_f32_32x32x16_bf16(vf, pa, o0, 0, 0, 0); }
;                     { const s16x4 lo = vtr(vb + 4096 + s * 1024), h4 = vtr(vb + 4096 + s * 1024 + 512);
;                       const bf16x8 vf = (bf16x8){lo[0], lo[1], lo[2], lo[3], h4[0], h4[1], h4[2], h4[3]};
;                       o1 = __builtin_amdgcn_mfma_f32_32x32x16_bf16(vf, pa, o1, 0, 0, 0); }
;                 }
.Lnb_even_norescale:
	v_sub_f32_e32 v80, v80, v202
	v_sub_f32_e32 v81, v81, v202
	v_sub_f32_e32 v82, v82, v202
	v_sub_f32_e32 v83, v83, v202
	v_sub_f32_e32 v84, v84, v202
	v_sub_f32_e32 v85, v85, v202
	v_sub_f32_e32 v86, v86, v202
	v_sub_f32_e32 v87, v87, v202
	v_sub_f32_e32 v88, v88, v202
	v_sub_f32_e32 v89, v89, v202
	v_sub_f32_e32 v90, v90, v202
	v_sub_f32_e32 v91, v91, v202
	v_sub_f32_e32 v92, v92, v202
	v_sub_f32_e32 v93, v93, v202
	v_sub_f32_e32 v94, v94, v202
	v_sub_f32_e32 v95, v95, v202
	v_sub_f32_e32 v48, v48, v202
	v_sub_f32_e32 v49, v49, v202
	v_sub_f32_e32 v50, v50, v202
	v_sub_f32_e32 v51, v51, v202
	v_mov_b32_e32 v42, 0
	v_mov_b32_e32 v43, 0
	v_exp_f32_e32 v80, v80
	v_exp_f32_e32 v81, v81
	v_exp_f32_e32 v82, v82
	v_exp_f32_e32 v83, v83
	v_exp_f32_e32 v84, v84
	v_exp_f32_e32 v85, v85
	v_exp_f32_e32 v86, v86
	v_exp_f32_e32 v87, v87
	s_nop 0
	v_cvt_pk_bf16_f32 v32, v80, v81
	v_cvt_pk_bf16_f32 v33, v82, v83
	v_cvt_pk_bf16_f32 v34, v84, v85
	v_cvt_pk_bf16_f32 v35, v86, v87
	s_nop 1
	s_waitcnt lgkmcnt(0)
	v_mfma_f32_32x32x16_bf16 v[0:15], v[160:163], v[32:35], v[0:15]
	v_exp_f32_e32 v88, v88
	v_exp_f32_e32 v89, v89
	v_exp_f32_e32 v90, v90
	v_exp_f32_e32 v91, v91
	v_mfma_f32_32x32x16_bf16 v[16:31], v[176:179], v[32:35], v[16:31]
	s_cmp_lg_u64 s[82:83], 0
	s_cbranch_scc0 .Lmkdk_even
	s_add_i32 s80, s32, 2
	s_cmp_ge_u32 s80, 3
	s_cselect_b32 s81, 3, 0
	s_sub_i32 s80, s80, s81
	s_lshl_b32 s81, s80, 13
	s_add_i32 s81, s81, s100
	s_mov_b32 m0, s81
	s_nop 0
	global_load_lds_dwordx4 v[112:113], off
	v_lshl_add_u64 v[112:113], v[112:113], 0, s[98:99]
.Lmkdk_even:
	v_exp_f32_e32 v92, v92
	v_exp_f32_e32 v93, v93
	v_exp_f32_e32 v94, v94
	v_exp_f32_e32 v95, v95
	s_nop 0
	v_cvt_pk_bf16_f32 v36, v88, v89
	v_cvt_pk_bf16_f32 v37, v90, v91
	v_cvt_pk_bf16_f32 v38, v92, v93
	v_cvt_pk_bf16_f32 v39, v94, v95
	v_mov_b32_e32 v204, v80
	v_mov_b32_e32 v205, v81
	v_mov_b32_e32 v208, v82
	v_mov_b32_e32 v209, v83
	v_add_f32_e32 v204, v204, v84
	v_add_f32_e32 v205, v205, v85
	v_add_f32_e32 v208, v208, v86
	v_add_f32_e32 v209, v209, v87
	v_mfma_f32_32x32x16_bf16 v[0:15], v[164:167], v[36:39], v[0:15]
	v_exp_f32_e32 v48, v48
	v_exp_f32_e32 v49, v49
	v_mfma_f32_32x32x16_bf16 v[16:31], v[180:183], v[36:39], v[16:31]
	s_cmp_lg_u64 s[82:83], 0
	s_cbranch_scc0 .Lmkdv_even
	s_add_i32 s80, s32, 2
	s_cmp_ge_u32 s80, 3
	s_cselect_b32 s81, 3, 0
	s_sub_i32 s80, s80, s81
	s_lshl_b32 s81, s80, 13
	s_add_i32 s96, s81, 0x6000
	s_cmp_eq_u32 s80, 2
	s_cselect_b32 s80, 0xc000, s96
	s_add_i32 s80, s80, s100
	s_mov_b32 m0, s80
	s_nop 0
	global_load_lds_dwordx4 v[114:115], off
	v_lshl_add_u64 v[114:115], v[114:115], 0, s[98:99]
.Lmkdv_even:
	v_exp_f32_e32 v50, v50
	v_exp_f32_e32 v51, v51
	s_nop 0
	v_cvt_pk_bf16_f32 v40, v48, v49
	v_cvt_pk_bf16_f32 v41, v50, v51
	v_add_f32_e32 v204, v204, v88
	v_add_f32_e32 v205, v205, v89
	v_add_f32_e32 v208, v208, v90
	v_add_f32_e32 v209, v209, v91
	v_add_f32_e32 v204, v204, v92
	v_add_f32_e32 v205, v205, v93
	v_add_f32_e32 v208, v208, v94
	v_add_f32_e32 v209, v209, v95
	v_mfma_f32_32x32x16_bf16 v[0:15], v[168:171], v[40:43], v[0:15]
	v_mfma_f32_32x32x16_bf16 v[16:31], v[184:187], v[40:43], v[16:31]
	v_add_f32_e32 v204, v204, v48
	v_add_f32_e32 v205, v205, v49
	v_add_f32_e32 v208, v208, v50
	v_add_f32_e32 v209, v209, v51
	v_add_f32_e32 v204, v204, v205
	v_add_f32_e32 v208, v208, v209
	v_add_f32_e32 v204, v204, v208
	v_add_f32_e32 v124, v124, v204
	s_branch .Lmsk_tail

; #define ATT_LAS __attribute__((address_space(3)))
; __device__ __forceinline__ unsigned pk_bf16(float lo, float hi) { unsigned r; asm volatile("v_cvt_pk_bf16_f32 %0, %1, %2" : "=v"(r) : "v"(lo), "v"(hi)); return r; }
; __device__ __forceinline__ void attn_unit(int uv, const float* sink_l, const bf16_t* P, bf16_t* Y, ATT_LAS unsigned char* lds, const float* rpb_l, const float* qn_l, const float* kn_l) {
;     ...
;                 float sum = 0.f;
; #pragma unroll
;                 for (int r = 0; r < 16; ++r) { p0[r] = __builtin_amdgcn_exp2f(p0[r] - m); p1[r] = __builtin_amdgcn_exp2f(p1[r] - m); sum += p0[r] + p1[r]; }
;                 lsum += sum;
;                 u32x4 pw[4];
; #pragma unroll
;                 for (int j = 0; j < 4; ++j) { pw[0][j] = pk_bf16(p0[2 * j], p0[2 * j + 1]); pw[1][j] = pk_bf16(p0[8 + 2 * j], p0[8 + 2 * j + 1]);
;                                               pw[2][j] = pk_bf16(p1[2 * j], p1[2 * j + 1]); pw[3][j] = pk_bf16(p1[8 + 2 * j], p1[8 + 2 * j + 1]); }
;                 const ATT_LAS unsigned char* vb = Vb + vlane;
; #pragma unroll
;                 for (int s = 0; s < 4; ++s) {
;                     const bf16x8 pa = __builtin_bit_cast(bf16x8, pw[s]);
;                     { const s16x4 lo = vtr(vb + s * 1024), h4 = vtr(vb + s * 1024 + 512);
;                       const bf16x8 vf = (bf16x8){lo[0], lo[1], lo[2], lo[3], h4[0], h4[1], h4[2], h4[3]};
;                       o0 = __builtin_amdgcn_mfma_f32_32x32x16_bf16(vf, pa, o0, 0, 0, 0); }
;                     { const s16x4 lo = vtr(vb + 4096 + s * 1024), h4 = vtr(vb + 4096 + s * 1024 + 512);
;                       const bf16x8 vf = (bf16x8){lo[0], lo[1], lo[2], lo[3], h4[0], h4[1], h4[2], h4[3]};
;                       o1 = __builtin_amdgcn_mfma_f32_32x32x16_bf16(vf, pa, o1, 0, 0, 0); }
;                 }
.Lnb_odd_norescale:
	v_sub_f32_e32 v92, v92, v202
	v_sub_f32_e32 v93, v93, v202
	v_sub_f32_e32 v94, v94, v202
	v_sub_f32_e32 v95, v95, v202
	v_sub_f32_e32 v48, v48, v202
	v_sub_f32_e32 v49, v49, v202
	v_sub_f32_e32 v50, v50, v202
	v_sub_f32_e32 v51, v51, v202
	v_sub_f32_e32 v52, v52, v202
	v_sub_f32_e32 v53, v53, v202
	v_sub_f32_e32 v54, v54, v202
	v_sub_f32_e32 v55, v55, v202
	v_sub_f32_e32 v56, v56, v202
	v_sub_f32_e32 v57, v57, v202
	v_sub_f32_e32 v58, v58, v202
	v_sub_f32_e32 v59, v59, v202
	v_sub_f32_e32 v60, v60, v202
	v_sub_f32_e32 v61, v61, v202
	v_sub_f32_e32 v62, v62, v202
	v_sub_f32_e32 v63, v63, v202
	v_mov_b32_e32 v36, 0
	v_mov_b32_e32 v37, 0
	v_exp_f32_e32 v92, v92
	v_exp_f32_e32 v93, v93
	v_exp_f32_e32 v94, v94
	v_exp_f32_e32 v95, v95
	s_nop 0
	v_cvt_pk_bf16_f32 v38, v92, v93
	v_cvt_pk_bf16_f32 v39, v94, v95
	s_nop 1
	s_waitcnt lgkmcnt(0)
	v_mfma_f32_32x32x16_bf16 v[0:15], v[164:167], v[36:39], v[0:15]
	v_exp_f32_e32 v48, v48
	v_exp_f32_e32 v49, v49
	v_exp_f32_e32 v50, v50
	v_exp_f32_e32 v51, v51
	v_mfma_f32_32x32x16_bf16 v[16:31], v[180:183], v[36:39], v[16:31]
	s_cmp_lg_u64 s[82:83], 0
	s_cbranch_scc0 .Lmkdk_odd
	s_add_i32 s80, s32, 2
	s_cmp_ge_u32 s80, 3
	s_cselect_b32 s81, 3, 0
	s_sub_i32 s80, s80, s81
	s_lshl_b32 s81, s80, 13
	s_add_i32 s81, s81, s100
	s_mov_b32 m0, s81
	s_nop 0
	global_load_lds_dwordx4 v[112:113], off
	v_lshl_add_u64 v[112:113], v[112:113], 0, s[98:99]
.Lmkdk_odd:
	v_exp_f32_e32 v52, v52
	v_exp_f32_e32 v53, v53
	v_exp_f32_e32 v54, v54
	v_exp_f32_e32 v55, v55
	s_nop 0
	v_cvt_pk_bf16_f32 v40, v48, v49
	v_cvt_pk_bf16_f32 v41, v50, v51
	v_cvt_pk_bf16_f32 v42, v52, v53
	v_cvt_pk_bf16_f32 v43, v54, v55
	v_mov_b32_e32 v204, v92
	v_mov_b32_e32 v205, v93
	v_mov_b32_e32 v208, v94
	v_mov_b32_e32 v209, v95
	v_mfma_f32_32x32x16_bf16 v[0:15], v[168:171], v[40:43], v[0:15]
	v_exp_f32_e32 v56, v56
	v_exp_f32_e32 v57, v57
	v_exp_f32_e32 v58, v58
	v_exp_f32_e32 v59, v59
	v_mfma_f32_32x32x16_bf16 v[16:31], v[184:187], v[40:43], v[16:31]
	s_cmp_lg_u64 s[82:83], 0
	s_cbranch_scc0 .Lmkdv_odd
	s_add_i32 s80, s32, 2
	s_cmp_ge_u32 s80, 3
	s_cselect_b32 s81, 3, 0
	s_sub_i32 s80, s80, s81
	s_lshl_b32 s81, s80, 13
	s_add_i32 s96, s81, 0x6000
	s_cmp_eq_u32 s80, 2
	s_cselect_b32 s80, 0xc000, s96
	s_add_i32 s80, s80, s100
	s_mov_b32 m0, s80
	s_nop 0
	global_load_lds_dwordx4 v[114:115], off
	v_lshl_add_u64 v[114:115], v[114:115], 0, s[98:99]
.Lmkdv_odd:
	v_exp_f32_e32 v60, v60
	v_exp_f32_e32 v61, v61
	v_exp_f32_e32 v62, v62
	v_exp_f32_e32 v63, v63
	s_nop 0
	v_cvt_pk_bf16_f32 v44, v56, v57
	v_cvt_pk_bf16_f32 v45, v58, v59
	v_cvt_pk_bf16_f32 v46, v60, v61
	v_cvt_pk_bf16_f32 v47, v62, v63
	v_add_f32_e32 v204, v204, v48
	v_add_f32_e32 v205, v205, v49
	v_add_f32_e32 v208, v208, v50
	v_add_f32_e32 v209, v209, v51
	v_add_f32_e32 v204, v204, v52
	v_add_f32_e32 v205, v205, v53
	v_add_f32_e32 v208, v208, v54
	v_add_f32_e32 v209, v209, v55
	v_mfma_f32_32x32x16_bf16 v[0:15], v[172:175], v[44:47], v[0:15]
	v_mfma_f32_32x32x16_bf16 v[16:31], v[188:191], v[44:47], v[16:31]
	v_add_f32_e32 v204, v204, v56
	v_add_f32_e32 v205, v205, v57
	v_add_f32_e32 v208, v208, v58
	v_add_f32_e32 v209, v209, v59
	v_add_f32_e32 v204, v204, v60
	v_add_f32_e32 v205, v205, v61
	v_add_f32_e32 v208, v208, v62
	v_add_f32_e32 v209, v209, v63
	v_add_f32_e32 v204, v204, v205
	v_add_f32_e32 v208, v208, v209
	v_add_f32_e32 v204, v204, v208
	v_add_f32_e32 v124, v124, v204
	s_branch .Lmsk_tail

; #define ATT_LAS __attribute__((address_space(3)))
; __device__ __forceinline__ void attn_unit(int uv, const float* sink_l, const bf16_t* P, bf16_t* Y, ATT_LAS unsigned char* lds, const float* rpb_l, const float* qn_l, const float* kn_l) {
;     ...
;         for (int t = 0; t < nlat; ++t) {
;             const int cur = t & 1, tl = a.t_lo + t;
;             if (t + 1 < nlat) { const size_t ro = (size_t)ATT_TROW(t + 5) * PITCH; kreg = *(const u32x4*)(kg + ro); vreg = *(const u32x4*)(vg + ro); }
;             bool need;
;             if (a.mode == 1) need = (tl * 64 + 63 >= qw - 128) && (tl * 64 <= qw + 31 + 128);
;             else { const int rs = clampi(qr - 4, 0, 120); need = (tl >= rs) && (tl < rs + 8); }
;     ...
;             if (t + 1 < nlat) { *(ATT_LAS u32x4*)(ATT_KBUF(cur ^ 1) + koff) = kreg; *(ATT_LAS u32x4*)(ATT_VBUF(cur ^ 1) + voff) = vreg; }
;             __syncthreads();
.Lmk_skip:
	s_cmp_lg_u64 s[82:83], 0
	s_cbranch_scc0 .Lmkdk_skip
	s_add_i32 s80, s32, 2
	s_cmp_ge_u32 s80, 3
	s_cselect_b32 s81, 3, 0
	s_sub_i32 s80, s80, s81
	s_lshl_b32 s81, s80, 13
	s_add_i32 s81, s81, s100
	s_mov_b32 m0, s81
	s_nop 0
	global_load_lds_dwordx4 v[112:113], off
	v_lshl_add_u64 v[112:113], v[112:113], 0, s[98:99]
.Lmkdk_skip:
	s_cmp_lg_u64 s[82:83], 0
	s_cbranch_scc0 .Lmkdv_skip
	s_add_i32 s80, s32, 2
	s_cmp_ge_u32 s80, 3
	s_cselect_b32 s81, 3, 0
	s_sub_i32 s80, s80, s81
	s_lshl_b32 s81, s80, 13
	s_add_i32 s96, s81, 0x6000
	s_cmp_eq_u32 s80, 2
	s_cselect_b32 s80, 0xc000, s96
	s_add_i32 s80, s80, s100
	s_mov_b32 m0, s80
	s_nop 0
	global_load_lds_dwordx4 v[114:115], off
	v_lshl_add_u64 v[114:115], v[114:115], 0, s[98:99]
.Lmkdv_skip:
.Lmsk_tail:
	s_add_i32 s92, s92, 64
	v_add_u32_e32 v127, 0x7c, v127
	s_add_i32 s7, s7, 1
	s_add_i32 s32, s32, 1
	s_cmp_eq_u32 s32, 3
	s_cselect_b32 s32, 0, s32
	s_and_b64 vcc, exec, s[82:83]
	s_cbranch_vccz .Lmk_w0
	s_waitcnt vmcnt(2)
	s_branch .Lmk_w1

; __device__ __forceinline__ unsigned xb_add(unsigned* p, unsigned v) { return __hip_atomic_fetch_add(p, v, __ATOMIC_RELAXED, __HIP_MEMORY_SCOPE_AGENT); }
; __device__ __forceinline__ void xcd_barrier(const XcdBarrier& b) {
;     asm volatile("s_waitcnt vmcnt(0)" ::: "memory");
;     __syncthreads();
;     if (threadIdx.x == 0) {
;         unsigned* bar = b.bar;
;         __builtin_amdgcn_s_waitcnt(0);
;         unsigned nloc = b.st[0], nx = b.st[1];
;         if (nloc == 0u) { xcd_barrier_complete(bar, b.x, nloc, nx); b.st[0] = nloc; b.st[1] = nx; }
;         const unsigned old = xb_add(&bar[XB_XSUB(b.x)], 1u);
.LBB0_699:
	s_lshl_b32 s2, s93, 6
	s_add_i32 s2, s2, s27
	s_add_i32 s2, s2, 64
	v_mad_i64_i32 v[32:33], s[2:3], s2, v215, v[198:199]
	global_load_dwordx4 v[120:123], v[32:33], off
	s_andn2_b64 vcc, exec, s[0:1]
	s_cbranch_vccz .LBB0_622
	s_branch .LBB0_623
	s_nop 0
	s_nop 0
	s_nop 0
	s_nop 0
	s_nop 0
	s_nop 0
	s_nop 0
	s_nop 0
	s_nop 0
	s_nop 0
	s_nop 0
	s_nop 0
	s_nop 0
	s_nop 0
	s_nop 0
	s_nop 0
	s_nop 0
	s_nop 0
	s_nop 0
	s_nop 0
	s_nop 0
	s_nop 0
	s_nop 0
	s_nop 0
	s_nop 0
	s_nop 0
	s_nop 0
	s_nop 0
	s_nop 0
.LBB0_700:
	s_mov_b32 s0, 0
	s_add_i32 s21, s0, 0
	s_add_i32 s0, s21, 0x200b8
	v_mov_b32_e32 v0, s0
	ds_read_b64 v[0:1], v0
	s_getreg_b32 s2, hwreg(HW_REG_XCC_ID, 0, 4)
	s_waitcnt vmcnt(0)
	s_waitcnt lgkmcnt(0)
	s_barrier
	v_readfirstlane_b32 s5, v1
	v_readfirstlane_b32 s4, v0
	s_mov_b64 s[0:1], exec
	v_readlane_b32 s6, v255, 0
	v_readlane_b32 s7, v255, 1
	s_and_b64 s[6:7], s[0:1], s[6:7]
	v_readlane_b32 s79, v255, 4
	s_mov_b32 s80, 0x20000
	s_movk_i32 s81, 0x2000
	s_movk_i32 s83, 0x1000
	s_mov_b32 s84, 0x400000
	s_mov_b32 s85, 0x800000
	s_mov_b32 s86, 0xc00000
	s_mov_b32 s87, 0xf800000
	s_mov_b32 s95, 0x40000
	s_mov_b32 s91, 0x60000
	s_movk_i32 s74, 0x16c
	s_mov_b32 s92, 0x10000
	s_movk_i32 s93, 0xffbf
	s_mov_b32 s94, 0x30000
	s_mov_b32 s76, 0x80000
	s_mov_b32 s77, 0x90000
	s_mov_b64 exec, s[6:7]
	s_cbranch_execz .LBB0_752
	s_add_i32 s22, s21, 0x20100
	v_mov_b32_e32 v0, s22
	s_add_i32 s21, s21, 0x20104
	s_waitcnt vmcnt(0) expcnt(0) lgkmcnt(0)
	ds_read_b32 v2, v0
	v_mov_b32_e32 v0, s21
	ds_read_b32 v0, v0
	s_and_b32 s20, s2, 15
	s_add_u32 s2, s4, 0x200
	s_waitcnt lgkmcnt(1)
	v_cmp_ne_u32_e32 vcc, 0, v2
	s_addc_u32 s3, s5, 0
	s_cbranch_vccnz .LBB0_716
	s_add_u32 s6, s4, 0x1000
	s_addc_u32 s7, s5, 0
	s_add_u32 s8, s4, 0x1100
	s_addc_u32 s9, s5, 0
	s_add_u32 s10, s4, 0x1200
	s_addc_u32 s11, s5, 0
	s_add_u32 s12, s4, 0x1300
	s_addc_u32 s13, s5, 0
	s_mov_b32 s23, 1
	s_branch .LBB0_704
